# up-proj epilogue: packed f32 VALU ops (v_pk_mul/fma/add) split into scalar pairs (cheaper beside the partner wave's MFMAs)
# baseline (speedup 1.0000x reference)
.Lup_en_cont:
	v_add_u32_e32 v216, 0x13010, v228
	ds_read_b128 v[178:181], v216 offset:0
	ds_read_b128 v[182:185], v216 offset:16
	ds_read_b128 v[186:189], v216 offset:256
	ds_read_b128 v[190:193], v216 offset:272
	ds_read_b128 v[194:197], v216 offset:512
	ds_read_b128 v[198:201], v216 offset:528
	ds_read_b128 v[202:205], v216 offset:768
	ds_read_b128 v[206:209], v216 offset:784
	s_lshl_b32 s26, s21, 1
	s_add_i32 s26, s26, s43
	s_lshl_b32 s26, s26, 20
	s_lshl_b32 s27, s35, 6
	s_add_u32 s18, s52, s26
	s_addc_u32 s19, s53, 0
	s_add_u32 s18, s18, s27
	s_addc_u32 s19, s19, 0
	s_add_u32 s6, s18, 0x1000
	s_addc_u32 s7, s19, 0
	s_waitcnt lgkmcnt(0)
	v_mov_b32_dpp v210, v98 row_ror:1 row_mask:0xf bank_mask:0xf
	v_mov_b32_dpp v212, v98 row_ror:2 row_mask:0xf bank_mask:0xf
	v_mov_b32_dpp v211, v99 row_ror:1 row_mask:0xf bank_mask:0xf
	v_mov_b32_dpp v213, v99 row_ror:2 row_mask:0xf bank_mask:0xf
	s_nop 1
	v_mov_b32_dpp v210, v114 row_shr:1 row_mask:0xf bank_mask:0xf
	v_mov_b32_dpp v212, v114 row_shr:2 row_mask:0xf bank_mask:0xf
	v_mov_b32_dpp v211, v115 row_shr:1 row_mask:0xf bank_mask:0xf
	v_mov_b32_dpp v213, v115 row_shr:2 row_mask:0xf bank_mask:0xf
	s_nop 1
	v_mul_f32_e32 v210, v186, v210
	v_mul_f32_e32 v211, v187, v211
	v_fma_f32 v214, v194, v114, v210
	v_fma_f32 v215, v195, v115, v211
	v_fma_f32 v214, v178, v212, v214
	v_fma_f32 v215, v179, v213, v215
	v_add_f32_e32 v214, v202, v214
	v_add_f32_e32 v215, v203, v215
	v_mul_f32_e32 v216, s92, v214
	v_mul_f32_e32 v217, s93, v215
	v_mul_f32_e32 v216, v214, v216
	v_mul_f32_e32 v217, v215, v217
	v_fma_f32 v216, v214, v216, v214
	v_fma_f32 v217, v215, v217, v215
	v_mul_f32_e32 v216, s96, v216
	v_mul_f32_e32 v217, s97, v217
	v_mul_f32_e32 v216, s28, v216
	v_mul_f32_e32 v217, s29, v217
	v_exp_f32_e32 v216, v216
	v_exp_f32_e32 v217, v217
	s_nop 0
	v_add_f32_e32 v216, 1.0, v216
	v_add_f32_e32 v217, 1.0, v217
	v_rcp_f32_e32 v216, v216
	v_rcp_f32_e32 v217, v217
	s_nop 0
	v_mul_f32_e32 v214, v214, v216
	v_mul_f32_e32 v215, v215, v217
	v_mul_f32_e32 v214, v122, v214
	v_mul_f32_e32 v215, v123, v215
	v_cvt_pk_bf16_f32 v122, v214, v215
	v_mov_b32_dpp v210, v100 row_ror:1 row_mask:0xf bank_mask:0xf
	v_mov_b32_dpp v212, v100 row_ror:2 row_mask:0xf bank_mask:0xf
	v_mov_b32_dpp v211, v101 row_ror:1 row_mask:0xf bank_mask:0xf
	v_mov_b32_dpp v213, v101 row_ror:2 row_mask:0xf bank_mask:0xf
	s_nop 1
	v_mov_b32_dpp v210, v116 row_shr:1 row_mask:0xf bank_mask:0xf
	v_mov_b32_dpp v212, v116 row_shr:2 row_mask:0xf bank_mask:0xf
	v_mov_b32_dpp v211, v117 row_shr:1 row_mask:0xf bank_mask:0xf
	v_mov_b32_dpp v213, v117 row_shr:2 row_mask:0xf bank_mask:0xf
	s_nop 1
	v_mul_f32_e32 v210, v188, v210
	v_mul_f32_e32 v211, v189, v211
	v_fma_f32 v214, v196, v116, v210
	v_fma_f32 v215, v197, v117, v211
	v_fma_f32 v214, v180, v212, v214
	v_fma_f32 v215, v181, v213, v215
	v_add_f32_e32 v214, v204, v214
	v_add_f32_e32 v215, v205, v215
	v_mul_f32_e32 v216, s92, v214
	v_mul_f32_e32 v217, s93, v215
	v_mul_f32_e32 v216, v214, v216
	v_mul_f32_e32 v217, v215, v217
	v_fma_f32 v216, v214, v216, v214
	v_fma_f32 v217, v215, v217, v215
	v_mul_f32_e32 v216, s96, v216
	v_mul_f32_e32 v217, s97, v217
	v_mul_f32_e32 v216, s28, v216
	v_mul_f32_e32 v217, s29, v217
	v_exp_f32_e32 v216, v216
	v_exp_f32_e32 v217, v217
	s_nop 0
	v_add_f32_e32 v216, 1.0, v216
	v_add_f32_e32 v217, 1.0, v217
	v_rcp_f32_e32 v216, v216
	v_rcp_f32_e32 v217, v217
	s_nop 0
	v_mul_f32_e32 v214, v214, v216
	v_mul_f32_e32 v215, v215, v217
	v_mul_f32_e32 v214, v124, v214
	v_mul_f32_e32 v215, v125, v215
	v_cvt_pk_bf16_f32 v123, v214, v215
	v_mov_b32_dpp v210, v102 row_ror:1 row_mask:0xf bank_mask:0xf
	v_mov_b32_dpp v212, v102 row_ror:2 row_mask:0xf bank_mask:0xf
	v_mov_b32_dpp v211, v103 row_ror:1 row_mask:0xf bank_mask:0xf
	v_mov_b32_dpp v213, v103 row_ror:2 row_mask:0xf bank_mask:0xf
	s_nop 1
	v_mov_b32_dpp v210, v118 row_shr:1 row_mask:0xf bank_mask:0xf
	v_mov_b32_dpp v212, v118 row_shr:2 row_mask:0xf bank_mask:0xf
	v_mov_b32_dpp v211, v119 row_shr:1 row_mask:0xf bank_mask:0xf
	v_mov_b32_dpp v213, v119 row_shr:2 row_mask:0xf bank_mask:0xf
	s_nop 1
	v_mul_f32_e32 v210, v190, v210
	v_mul_f32_e32 v211, v191, v211
	v_fma_f32 v214, v198, v118, v210
	v_fma_f32 v215, v199, v119, v211
	v_fma_f32 v214, v182, v212, v214
	v_fma_f32 v215, v183, v213, v215
	v_add_f32_e32 v214, v206, v214
	v_add_f32_e32 v215, v207, v215
	v_mul_f32_e32 v216, s92, v214
	v_mul_f32_e32 v217, s93, v215
	v_mul_f32_e32 v216, v214, v216
	v_mul_f32_e32 v217, v215, v217
	v_fma_f32 v216, v214, v216, v214
	v_fma_f32 v217, v215, v217, v215
	v_mul_f32_e32 v216, s96, v216
	v_mul_f32_e32 v217, s97, v217
	v_mul_f32_e32 v216, s28, v216
	v_mul_f32_e32 v217, s29, v217
	v_exp_f32_e32 v216, v216
	v_exp_f32_e32 v217, v217
	s_nop 0
	v_add_f32_e32 v216, 1.0, v216
	v_add_f32_e32 v217, 1.0, v217
	v_rcp_f32_e32 v216, v216
	v_rcp_f32_e32 v217, v217
	s_nop 0
	v_mul_f32_e32 v214, v214, v216
	v_mul_f32_e32 v215, v215, v217
	v_mul_f32_e32 v214, v126, v214
	v_mul_f32_e32 v215, v127, v215
	v_cvt_pk_bf16_f32 v124, v214, v215
	v_mov_b32_dpp v210, v104 row_ror:1 row_mask:0xf bank_mask:0xf
	v_mov_b32_dpp v212, v104 row_ror:2 row_mask:0xf bank_mask:0xf
	v_mov_b32_dpp v211, v105 row_ror:1 row_mask:0xf bank_mask:0xf
	v_mov_b32_dpp v213, v105 row_ror:2 row_mask:0xf bank_mask:0xf
	s_nop 1
	v_mov_b32_dpp v210, v120 row_shr:1 row_mask:0xf bank_mask:0xf
	v_mov_b32_dpp v212, v120 row_shr:2 row_mask:0xf bank_mask:0xf
	v_mov_b32_dpp v211, v121 row_shr:1 row_mask:0xf bank_mask:0xf
	v_mov_b32_dpp v213, v121 row_shr:2 row_mask:0xf bank_mask:0xf
	s_nop 1
	v_mul_f32_e32 v210, v192, v210
	v_mul_f32_e32 v211, v193, v211
	v_fma_f32 v214, v200, v120, v210
	v_fma_f32 v215, v201, v121, v211
	v_fma_f32 v214, v184, v212, v214
	v_fma_f32 v215, v185, v213, v215
	v_add_f32_e32 v214, v208, v214
	v_add_f32_e32 v215, v209, v215
	v_mul_f32_e32 v216, s92, v214
	v_mul_f32_e32 v217, s93, v215
	v_mul_f32_e32 v216, v214, v216
	v_mul_f32_e32 v217, v215, v217
	v_fma_f32 v216, v214, v216, v214
	v_fma_f32 v217, v215, v217, v215
	v_mul_f32_e32 v216, s96, v216
	v_mul_f32_e32 v217, s97, v217
	v_mul_f32_e32 v216, s28, v216
	v_mul_f32_e32 v217, s29, v217
	v_exp_f32_e32 v216, v216
	v_exp_f32_e32 v217, v217
	s_nop 0
	v_add_f32_e32 v216, 1.0, v216
	v_add_f32_e32 v217, 1.0, v217
	v_rcp_f32_e32 v216, v216
	v_rcp_f32_e32 v217, v217
	s_nop 0
	v_mul_f32_e32 v214, v214, v216
	v_mul_f32_e32 v215, v215, v217
	v_mul_f32_e32 v214, v128, v214
	v_mul_f32_e32 v215, v129, v215
	v_cvt_pk_bf16_f32 v125, v214, v215
	global_store_dwordx4 v242, v[122:125], s[6:7] offset:3072
	v_mov_b32_dpp v210, v82 row_ror:1 row_mask:0xf bank_mask:0xf
	v_mov_b32_dpp v212, v82 row_ror:2 row_mask:0xf bank_mask:0xf
	v_mov_b32_dpp v211, v83 row_ror:1 row_mask:0xf bank_mask:0xf
	v_mov_b32_dpp v213, v83 row_ror:2 row_mask:0xf bank_mask:0xf
	s_nop 1
	v_mov_b32_dpp v210, v98 row_shr:1 row_mask:0xf bank_mask:0xf
	v_mov_b32_dpp v212, v98 row_shr:2 row_mask:0xf bank_mask:0xf
	v_mov_b32_dpp v211, v99 row_shr:1 row_mask:0xf bank_mask:0xf
	v_mov_b32_dpp v213, v99 row_shr:2 row_mask:0xf bank_mask:0xf
	s_nop 1
	v_mul_f32_e32 v210, v186, v210
	v_mul_f32_e32 v211, v187, v211
	v_fma_f32 v214, v194, v98, v210
	v_fma_f32 v215, v195, v99, v211
	v_fma_f32 v214, v178, v212, v214
	v_fma_f32 v215, v179, v213, v215
	v_add_f32_e32 v214, v202, v214
	v_add_f32_e32 v215, v203, v215
	v_mul_f32_e32 v216, s92, v214
	v_mul_f32_e32 v217, s93, v215
	v_mul_f32_e32 v216, v214, v216
	v_mul_f32_e32 v217, v215, v217
	v_fma_f32 v216, v214, v216, v214
	v_fma_f32 v217, v215, v217, v215
	v_mul_f32_e32 v216, s96, v216
	v_mul_f32_e32 v217, s97, v217
	v_mul_f32_e32 v216, s28, v216
	v_mul_f32_e32 v217, s29, v217
	v_exp_f32_e32 v216, v216
	v_exp_f32_e32 v217, v217
	s_nop 0
	v_add_f32_e32 v216, 1.0, v216
	v_add_f32_e32 v217, 1.0, v217
	v_rcp_f32_e32 v216, v216
	v_rcp_f32_e32 v217, v217
	s_nop 0
	v_mul_f32_e32 v214, v214, v216
	v_mul_f32_e32 v215, v215, v217
	v_mul_f32_e32 v214, v106, v214
	v_mul_f32_e32 v215, v107, v215
	v_cvt_pk_bf16_f32 v106, v214, v215
	v_mov_b32_dpp v210, v84 row_ror:1 row_mask:0xf bank_mask:0xf
	v_mov_b32_dpp v212, v84 row_ror:2 row_mask:0xf bank_mask:0xf
	v_mov_b32_dpp v211, v85 row_ror:1 row_mask:0xf bank_mask:0xf
	v_mov_b32_dpp v213, v85 row_ror:2 row_mask:0xf bank_mask:0xf
	s_nop 1
	v_mov_b32_dpp v210, v100 row_shr:1 row_mask:0xf bank_mask:0xf
	v_mov_b32_dpp v212, v100 row_shr:2 row_mask:0xf bank_mask:0xf
	v_mov_b32_dpp v211, v101 row_shr:1 row_mask:0xf bank_mask:0xf
	v_mov_b32_dpp v213, v101 row_shr:2 row_mask:0xf bank_mask:0xf
	s_nop 1
	v_mul_f32_e32 v210, v188, v210
	v_mul_f32_e32 v211, v189, v211
	v_fma_f32 v214, v196, v100, v210
	v_fma_f32 v215, v197, v101, v211
	v_fma_f32 v214, v180, v212, v214
	v_fma_f32 v215, v181, v213, v215
	v_add_f32_e32 v214, v204, v214
	v_add_f32_e32 v215, v205, v215
	v_mul_f32_e32 v216, s92, v214
	v_mul_f32_e32 v217, s93, v215
	v_mul_f32_e32 v216, v214, v216
	v_mul_f32_e32 v217, v215, v217
	v_fma_f32 v216, v214, v216, v214
	v_fma_f32 v217, v215, v217, v215
	v_mul_f32_e32 v216, s96, v216
	v_mul_f32_e32 v217, s97, v217
	v_mul_f32_e32 v216, s28, v216
	v_mul_f32_e32 v217, s29, v217
	v_exp_f32_e32 v216, v216
	v_exp_f32_e32 v217, v217
	s_nop 0
	v_add_f32_e32 v216, 1.0, v216
	v_add_f32_e32 v217, 1.0, v217
	v_rcp_f32_e32 v216, v216
	v_rcp_f32_e32 v217, v217
	s_nop 0
	v_mul_f32_e32 v214, v214, v216
	v_mul_f32_e32 v215, v215, v217
	v_mul_f32_e32 v214, v108, v214
	v_mul_f32_e32 v215, v109, v215
	v_cvt_pk_bf16_f32 v107, v214, v215
	v_mov_b32_dpp v210, v86 row_ror:1 row_mask:0xf bank_mask:0xf
	v_mov_b32_dpp v212, v86 row_ror:2 row_mask:0xf bank_mask:0xf
	v_mov_b32_dpp v211, v87 row_ror:1 row_mask:0xf bank_mask:0xf
	v_mov_b32_dpp v213, v87 row_ror:2 row_mask:0xf bank_mask:0xf
	s_nop 1
	v_mov_b32_dpp v210, v102 row_shr:1 row_mask:0xf bank_mask:0xf
	v_mov_b32_dpp v212, v102 row_shr:2 row_mask:0xf bank_mask:0xf
	v_mov_b32_dpp v211, v103 row_shr:1 row_mask:0xf bank_mask:0xf
	v_mov_b32_dpp v213, v103 row_shr:2 row_mask:0xf bank_mask:0xf
	s_nop 1
	v_mul_f32_e32 v210, v190, v210
	v_mul_f32_e32 v211, v191, v211
	v_fma_f32 v214, v198, v102, v210
	v_fma_f32 v215, v199, v103, v211
	v_fma_f32 v214, v182, v212, v214
	v_fma_f32 v215, v183, v213, v215
	v_add_f32_e32 v214, v206, v214
	v_add_f32_e32 v215, v207, v215
	v_mul_f32_e32 v216, s92, v214
	v_mul_f32_e32 v217, s93, v215
	v_mul_f32_e32 v216, v214, v216
	v_mul_f32_e32 v217, v215, v217
	v_fma_f32 v216, v214, v216, v214
	v_fma_f32 v217, v215, v217, v215
	v_mul_f32_e32 v216, s96, v216
	v_mul_f32_e32 v217, s97, v217
	v_mul_f32_e32 v216, s28, v216
	v_mul_f32_e32 v217, s29, v217
	v_exp_f32_e32 v216, v216
	v_exp_f32_e32 v217, v217
	s_nop 0
	v_add_f32_e32 v216, 1.0, v216
	v_add_f32_e32 v217, 1.0, v217
	v_rcp_f32_e32 v216, v216
	v_rcp_f32_e32 v217, v217
	s_nop 0
	v_mul_f32_e32 v214, v214, v216
	v_mul_f32_e32 v215, v215, v217
	v_mul_f32_e32 v214, v110, v214
	v_mul_f32_e32 v215, v111, v215
	v_cvt_pk_bf16_f32 v108, v214, v215
	v_mov_b32_dpp v210, v88 row_ror:1 row_mask:0xf bank_mask:0xf
	v_mov_b32_dpp v212, v88 row_ror:2 row_mask:0xf bank_mask:0xf
	v_mov_b32_dpp v211, v89 row_ror:1 row_mask:0xf bank_mask:0xf
	v_mov_b32_dpp v213, v89 row_ror:2 row_mask:0xf bank_mask:0xf
	s_nop 1
	v_mov_b32_dpp v210, v104 row_shr:1 row_mask:0xf bank_mask:0xf
	v_mov_b32_dpp v212, v104 row_shr:2 row_mask:0xf bank_mask:0xf
	v_mov_b32_dpp v211, v105 row_shr:1 row_mask:0xf bank_mask:0xf
	v_mov_b32_dpp v213, v105 row_shr:2 row_mask:0xf bank_mask:0xf
	s_nop 1
	v_mul_f32_e32 v210, v192, v210
	v_mul_f32_e32 v211, v193, v211
	v_fma_f32 v214, v200, v104, v210
	v_fma_f32 v215, v201, v105, v211
	v_fma_f32 v214, v184, v212, v214
	v_fma_f32 v215, v185, v213, v215
	v_add_f32_e32 v214, v208, v214
	v_add_f32_e32 v215, v209, v215
	v_mul_f32_e32 v216, s92, v214
	v_mul_f32_e32 v217, s93, v215
	v_mul_f32_e32 v216, v214, v216
	v_mul_f32_e32 v217, v215, v217
	v_fma_f32 v216, v214, v216, v214
	v_fma_f32 v217, v215, v217, v215
	v_mul_f32_e32 v216, s96, v216
	v_mul_f32_e32 v217, s97, v217
	v_mul_f32_e32 v216, s28, v216
	v_mul_f32_e32 v217, s29, v217
	v_exp_f32_e32 v216, v216
	v_exp_f32_e32 v217, v217
	s_nop 0
	v_add_f32_e32 v216, 1.0, v216
	v_add_f32_e32 v217, 1.0, v217
	v_rcp_f32_e32 v216, v216
	v_rcp_f32_e32 v217, v217
	s_nop 0
	v_mul_f32_e32 v214, v214, v216
	v_mul_f32_e32 v215, v215, v217
	v_mul_f32_e32 v214, v112, v214
	v_mul_f32_e32 v215, v113, v215
	v_cvt_pk_bf16_f32 v109, v214, v215
	global_store_dwordx4 v242, v[106:109], s[6:7] offset:2048
	s_waitcnt vmcnt(2)
	s_barrier
	s_cmp_eq_u32 s41, 2
	s_cbranch_scc0 .Lup_en_nf
	s_add_i32 s27, s34, 0xfffff600
	s_add_i32 s26, s34, 0x3600
	s_cmpk_lt_u32 s34, 0xa00
	s_cselect_b32 s27, s26, s27
	v_mov_b32_e32 v249, s27
	v_mov_b32_e32 v250, s20
	s_mov_b64 s[26:27], exec
	s_mov_b64 exec, 1
	global_store_byte v249, v250, s[64:65] sc0 sc1
	s_mov_b64 exec, s[26:27]
.Lup_en_nf:
	v_mov_b32_dpp v210, v66 row_ror:1 row_mask:0xf bank_mask:0xf
	v_mov_b32_dpp v212, v66 row_ror:2 row_mask:0xf bank_mask:0xf
	v_mov_b32_dpp v211, v67 row_ror:1 row_mask:0xf bank_mask:0xf
	v_mov_b32_dpp v213, v67 row_ror:2 row_mask:0xf bank_mask:0xf
	s_nop 1
	v_mov_b32_dpp v210, v82 row_shr:1 row_mask:0xf bank_mask:0xf
	v_mov_b32_dpp v212, v82 row_shr:2 row_mask:0xf bank_mask:0xf
	v_mov_b32_dpp v211, v83 row_shr:1 row_mask:0xf bank_mask:0xf
	v_mov_b32_dpp v213, v83 row_shr:2 row_mask:0xf bank_mask:0xf
	s_nop 1
	v_mul_f32_e32 v210, v186, v210
	v_mul_f32_e32 v211, v187, v211
	v_fma_f32 v214, v194, v82, v210
	v_fma_f32 v215, v195, v83, v211
	v_fma_f32 v214, v178, v212, v214
	v_fma_f32 v215, v179, v213, v215
	v_add_f32_e32 v214, v202, v214
	v_add_f32_e32 v215, v203, v215
	v_mul_f32_e32 v216, s92, v214
	v_mul_f32_e32 v217, s93, v215
	v_mul_f32_e32 v216, v214, v216
	v_mul_f32_e32 v217, v215, v217
	v_fma_f32 v216, v214, v216, v214
	v_fma_f32 v217, v215, v217, v215
	v_mul_f32_e32 v216, s96, v216
	v_mul_f32_e32 v217, s97, v217
	v_mul_f32_e32 v216, s28, v216
	v_mul_f32_e32 v217, s29, v217
	v_exp_f32_e32 v216, v216
	v_exp_f32_e32 v217, v217
	s_nop 0
	v_add_f32_e32 v216, 1.0, v216
	v_add_f32_e32 v217, 1.0, v217
	v_rcp_f32_e32 v216, v216
	v_rcp_f32_e32 v217, v217
	s_nop 0
	v_mul_f32_e32 v214, v214, v216
	v_mul_f32_e32 v215, v215, v217
	v_mul_f32_e32 v214, v90, v214
	v_mul_f32_e32 v215, v91, v215
	v_cvt_pk_bf16_f32 v90, v214, v215
	v_mov_b32_dpp v210, v68 row_ror:1 row_mask:0xf bank_mask:0xf
	v_mov_b32_dpp v212, v68 row_ror:2 row_mask:0xf bank_mask:0xf
	v_mov_b32_dpp v211, v69 row_ror:1 row_mask:0xf bank_mask:0xf
	v_mov_b32_dpp v213, v69 row_ror:2 row_mask:0xf bank_mask:0xf
	s_nop 1
	v_mov_b32_dpp v210, v84 row_shr:1 row_mask:0xf bank_mask:0xf
	v_mov_b32_dpp v212, v84 row_shr:2 row_mask:0xf bank_mask:0xf
	v_mov_b32_dpp v211, v85 row_shr:1 row_mask:0xf bank_mask:0xf
	v_mov_b32_dpp v213, v85 row_shr:2 row_mask:0xf bank_mask:0xf
	s_nop 1
	v_mul_f32_e32 v210, v188, v210
	v_mul_f32_e32 v211, v189, v211
	v_fma_f32 v214, v196, v84, v210
	v_fma_f32 v215, v197, v85, v211
	v_fma_f32 v214, v180, v212, v214
	v_fma_f32 v215, v181, v213, v215
	v_add_f32_e32 v214, v204, v214
	v_add_f32_e32 v215, v205, v215
	v_mul_f32_e32 v216, s92, v214
	v_mul_f32_e32 v217, s93, v215
	v_mul_f32_e32 v216, v214, v216
	v_mul_f32_e32 v217, v215, v217
	v_fma_f32 v216, v214, v216, v214
	v_fma_f32 v217, v215, v217, v215
	v_mul_f32_e32 v216, s96, v216
	v_mul_f32_e32 v217, s97, v217
	v_mul_f32_e32 v216, s28, v216
	v_mul_f32_e32 v217, s29, v217
	v_exp_f32_e32 v216, v216
	v_exp_f32_e32 v217, v217
	s_nop 0
	v_add_f32_e32 v216, 1.0, v216
	v_add_f32_e32 v217, 1.0, v217
	v_rcp_f32_e32 v216, v216
	v_rcp_f32_e32 v217, v217
	s_nop 0
	v_mul_f32_e32 v214, v214, v216
	v_mul_f32_e32 v215, v215, v217
	v_mul_f32_e32 v214, v92, v214
	v_mul_f32_e32 v215, v93, v215
	v_cvt_pk_bf16_f32 v91, v214, v215
	v_mov_b32_dpp v210, v70 row_ror:1 row_mask:0xf bank_mask:0xf
	v_mov_b32_dpp v212, v70 row_ror:2 row_mask:0xf bank_mask:0xf
	v_mov_b32_dpp v211, v71 row_ror:1 row_mask:0xf bank_mask:0xf
	v_mov_b32_dpp v213, v71 row_ror:2 row_mask:0xf bank_mask:0xf
	s_nop 1
	v_mov_b32_dpp v210, v86 row_shr:1 row_mask:0xf bank_mask:0xf
	v_mov_b32_dpp v212, v86 row_shr:2 row_mask:0xf bank_mask:0xf
	v_mov_b32_dpp v211, v87 row_shr:1 row_mask:0xf bank_mask:0xf
	v_mov_b32_dpp v213, v87 row_shr:2 row_mask:0xf bank_mask:0xf
	s_nop 1
	v_mul_f32_e32 v210, v190, v210
	v_mul_f32_e32 v211, v191, v211
	v_fma_f32 v214, v198, v86, v210
	v_fma_f32 v215, v199, v87, v211
	v_fma_f32 v214, v182, v212, v214
	v_fma_f32 v215, v183, v213, v215
	v_add_f32_e32 v214, v206, v214
	v_add_f32_e32 v215, v207, v215
	v_mul_f32_e32 v216, s92, v214
	v_mul_f32_e32 v217, s93, v215
	v_mul_f32_e32 v216, v214, v216
	v_mul_f32_e32 v217, v215, v217
	v_fma_f32 v216, v214, v216, v214
	v_fma_f32 v217, v215, v217, v215
	v_mul_f32_e32 v216, s96, v216
	v_mul_f32_e32 v217, s97, v217
	v_mul_f32_e32 v216, s28, v216
	v_mul_f32_e32 v217, s29, v217
	v_exp_f32_e32 v216, v216
	v_exp_f32_e32 v217, v217
	s_nop 0
	v_add_f32_e32 v216, 1.0, v216
	v_add_f32_e32 v217, 1.0, v217
	v_rcp_f32_e32 v216, v216
	v_rcp_f32_e32 v217, v217
	s_nop 0
	v_mul_f32_e32 v214, v214, v216
	v_mul_f32_e32 v215, v215, v217
	v_mul_f32_e32 v214, v94, v214
	v_mul_f32_e32 v215, v95, v215
	v_cvt_pk_bf16_f32 v92, v214, v215
	v_mov_b32_dpp v210, v72 row_ror:1 row_mask:0xf bank_mask:0xf
	v_mov_b32_dpp v212, v72 row_ror:2 row_mask:0xf bank_mask:0xf
	v_mov_b32_dpp v211, v73 row_ror:1 row_mask:0xf bank_mask:0xf
	v_mov_b32_dpp v213, v73 row_ror:2 row_mask:0xf bank_mask:0xf
	s_nop 1
	v_mov_b32_dpp v210, v88 row_shr:1 row_mask:0xf bank_mask:0xf
	v_mov_b32_dpp v212, v88 row_shr:2 row_mask:0xf bank_mask:0xf
	v_mov_b32_dpp v211, v89 row_shr:1 row_mask:0xf bank_mask:0xf
	v_mov_b32_dpp v213, v89 row_shr:2 row_mask:0xf bank_mask:0xf
	s_nop 1
	v_mul_f32_e32 v210, v192, v210
	v_mul_f32_e32 v211, v193, v211
	v_fma_f32 v214, v200, v88, v210
	v_fma_f32 v215, v201, v89, v211
	v_fma_f32 v214, v184, v212, v214
	v_fma_f32 v215, v185, v213, v215
	v_add_f32_e32 v214, v208, v214
	v_add_f32_e32 v215, v209, v215
	v_mul_f32_e32 v216, s92, v214
	v_mul_f32_e32 v217, s93, v215
	v_mul_f32_e32 v216, v214, v216
	v_mul_f32_e32 v217, v215, v217
	v_fma_f32 v216, v214, v216, v214
	v_fma_f32 v217, v215, v217, v215
	v_mul_f32_e32 v216, s96, v216
	v_mul_f32_e32 v217, s97, v217
	v_mul_f32_e32 v216, s28, v216
	v_mul_f32_e32 v217, s29, v217
	v_exp_f32_e32 v216, v216
	v_exp_f32_e32 v217, v217
	s_nop 0
	v_add_f32_e32 v216, 1.0, v216
	v_add_f32_e32 v217, 1.0, v217
	v_rcp_f32_e32 v216, v216
	v_rcp_f32_e32 v217, v217
	s_nop 0
	v_mul_f32_e32 v214, v214, v216
	v_mul_f32_e32 v215, v215, v217
	v_mul_f32_e32 v214, v96, v214
	v_mul_f32_e32 v215, v97, v215
	v_cvt_pk_bf16_f32 v93, v214, v215
	global_store_dwordx4 v242, v[90:93], s[6:7] offset:1024
	v_mov_b32_dpp v210, v50 row_ror:1 row_mask:0xf bank_mask:0xf
	v_mov_b32_dpp v212, v50 row_ror:2 row_mask:0xf bank_mask:0xf
	v_mov_b32_dpp v211, v51 row_ror:1 row_mask:0xf bank_mask:0xf
	v_mov_b32_dpp v213, v51 row_ror:2 row_mask:0xf bank_mask:0xf
	s_nop 1
	v_mov_b32_dpp v210, v66 row_shr:1 row_mask:0xf bank_mask:0xf
	v_mov_b32_dpp v212, v66 row_shr:2 row_mask:0xf bank_mask:0xf
	v_mov_b32_dpp v211, v67 row_shr:1 row_mask:0xf bank_mask:0xf
	v_mov_b32_dpp v213, v67 row_shr:2 row_mask:0xf bank_mask:0xf
	s_nop 1
	v_mul_f32_e32 v210, v186, v210
	v_mul_f32_e32 v211, v187, v211
	v_fma_f32 v214, v194, v66, v210
	v_fma_f32 v215, v195, v67, v211
	v_fma_f32 v214, v178, v212, v214
	v_fma_f32 v215, v179, v213, v215
	v_add_f32_e32 v214, v202, v214
	v_add_f32_e32 v215, v203, v215
	v_mul_f32_e32 v216, s92, v214
	v_mul_f32_e32 v217, s93, v215
	v_mul_f32_e32 v216, v214, v216
	v_mul_f32_e32 v217, v215, v217
	v_fma_f32 v216, v214, v216, v214
	v_fma_f32 v217, v215, v217, v215
	v_mul_f32_e32 v216, s96, v216
	v_mul_f32_e32 v217, s97, v217
	v_mul_f32_e32 v216, s28, v216
	v_mul_f32_e32 v217, s29, v217
	v_exp_f32_e32 v216, v216
	v_exp_f32_e32 v217, v217
	s_nop 0
	v_add_f32_e32 v216, 1.0, v216
	v_add_f32_e32 v217, 1.0, v217
	v_rcp_f32_e32 v216, v216
	v_rcp_f32_e32 v217, v217
	s_nop 0
	v_mul_f32_e32 v214, v214, v216
	v_mul_f32_e32 v215, v215, v217
	v_mul_f32_e32 v214, v74, v214
	v_mul_f32_e32 v215, v75, v215
	v_cvt_pk_bf16_f32 v74, v214, v215
	v_mov_b32_dpp v210, v52 row_ror:1 row_mask:0xf bank_mask:0xf
	v_mov_b32_dpp v212, v52 row_ror:2 row_mask:0xf bank_mask:0xf
	v_mov_b32_dpp v211, v53 row_ror:1 row_mask:0xf bank_mask:0xf
	v_mov_b32_dpp v213, v53 row_ror:2 row_mask:0xf bank_mask:0xf
	s_nop 1
	v_mov_b32_dpp v210, v68 row_shr:1 row_mask:0xf bank_mask:0xf
	v_mov_b32_dpp v212, v68 row_shr:2 row_mask:0xf bank_mask:0xf
	v_mov_b32_dpp v211, v69 row_shr:1 row_mask:0xf bank_mask:0xf
	v_mov_b32_dpp v213, v69 row_shr:2 row_mask:0xf bank_mask:0xf
	s_nop 1
	v_mul_f32_e32 v210, v188, v210
	v_mul_f32_e32 v211, v189, v211
	v_fma_f32 v214, v196, v68, v210
	v_fma_f32 v215, v197, v69, v211
	v_fma_f32 v214, v180, v212, v214
	v_fma_f32 v215, v181, v213, v215
	v_add_f32_e32 v214, v204, v214
	v_add_f32_e32 v215, v205, v215
	v_mul_f32_e32 v216, s92, v214
	v_mul_f32_e32 v217, s93, v215
	v_mul_f32_e32 v216, v214, v216
	v_mul_f32_e32 v217, v215, v217
	v_fma_f32 v216, v214, v216, v214
	v_fma_f32 v217, v215, v217, v215
	v_mul_f32_e32 v216, s96, v216
	v_mul_f32_e32 v217, s97, v217
	v_mul_f32_e32 v216, s28, v216
	v_mul_f32_e32 v217, s29, v217
	v_exp_f32_e32 v216, v216
	v_exp_f32_e32 v217, v217
	s_nop 0
	v_add_f32_e32 v216, 1.0, v216
	v_add_f32_e32 v217, 1.0, v217
	v_rcp_f32_e32 v216, v216
	v_rcp_f32_e32 v217, v217
	s_nop 0
	v_mul_f32_e32 v214, v214, v216
	v_mul_f32_e32 v215, v215, v217
	v_mul_f32_e32 v214, v76, v214
	v_mul_f32_e32 v215, v77, v215
	v_cvt_pk_bf16_f32 v75, v214, v215
	v_mov_b32_dpp v210, v54 row_ror:1 row_mask:0xf bank_mask:0xf
	v_mov_b32_dpp v212, v54 row_ror:2 row_mask:0xf bank_mask:0xf
	v_mov_b32_dpp v211, v55 row_ror:1 row_mask:0xf bank_mask:0xf
	v_mov_b32_dpp v213, v55 row_ror:2 row_mask:0xf bank_mask:0xf
	s_nop 1
	v_mov_b32_dpp v210, v70 row_shr:1 row_mask:0xf bank_mask:0xf
	v_mov_b32_dpp v212, v70 row_shr:2 row_mask:0xf bank_mask:0xf
	v_mov_b32_dpp v211, v71 row_shr:1 row_mask:0xf bank_mask:0xf
	v_mov_b32_dpp v213, v71 row_shr:2 row_mask:0xf bank_mask:0xf
	s_nop 1
	v_mul_f32_e32 v210, v190, v210
	v_mul_f32_e32 v211, v191, v211
	v_fma_f32 v214, v198, v70, v210
	v_fma_f32 v215, v199, v71, v211
	v_fma_f32 v214, v182, v212, v214
	v_fma_f32 v215, v183, v213, v215
	v_add_f32_e32 v214, v206, v214
	v_add_f32_e32 v215, v207, v215
	v_mul_f32_e32 v216, s92, v214
	v_mul_f32_e32 v217, s93, v215
	v_mul_f32_e32 v216, v214, v216
	v_mul_f32_e32 v217, v215, v217
	v_fma_f32 v216, v214, v216, v214
	v_fma_f32 v217, v215, v217, v215
	v_mul_f32_e32 v216, s96, v216
	v_mul_f32_e32 v217, s97, v217
	v_mul_f32_e32 v216, s28, v216
	v_mul_f32_e32 v217, s29, v217
	v_exp_f32_e32 v216, v216
	v_exp_f32_e32 v217, v217
	s_nop 0
	v_add_f32_e32 v216, 1.0, v216
	v_add_f32_e32 v217, 1.0, v217
	v_rcp_f32_e32 v216, v216
	v_rcp_f32_e32 v217, v217
	s_nop 0
	v_mul_f32_e32 v214, v214, v216
	v_mul_f32_e32 v215, v215, v217
	v_mul_f32_e32 v214, v78, v214
	v_mul_f32_e32 v215, v79, v215
	v_cvt_pk_bf16_f32 v76, v214, v215
	v_mov_b32_dpp v210, v56 row_ror:1 row_mask:0xf bank_mask:0xf
	v_mov_b32_dpp v212, v56 row_ror:2 row_mask:0xf bank_mask:0xf
	v_mov_b32_dpp v211, v57 row_ror:1 row_mask:0xf bank_mask:0xf
	v_mov_b32_dpp v213, v57 row_ror:2 row_mask:0xf bank_mask:0xf
	s_nop 1
	v_mov_b32_dpp v210, v72 row_shr:1 row_mask:0xf bank_mask:0xf
	v_mov_b32_dpp v212, v72 row_shr:2 row_mask:0xf bank_mask:0xf
	v_mov_b32_dpp v211, v73 row_shr:1 row_mask:0xf bank_mask:0xf
	v_mov_b32_dpp v213, v73 row_shr:2 row_mask:0xf bank_mask:0xf
	s_nop 1
	v_mul_f32_e32 v210, v192, v210
	v_mul_f32_e32 v211, v193, v211
	v_fma_f32 v214, v200, v72, v210
	v_fma_f32 v215, v201, v73, v211
	v_fma_f32 v214, v184, v212, v214
	v_fma_f32 v215, v185, v213, v215
	v_add_f32_e32 v214, v208, v214
	v_add_f32_e32 v215, v209, v215
	v_mul_f32_e32 v216, s92, v214
	v_mul_f32_e32 v217, s93, v215
	v_mul_f32_e32 v216, v214, v216
	v_mul_f32_e32 v217, v215, v217
	v_fma_f32 v216, v214, v216, v214
	v_fma_f32 v217, v215, v217, v215
	v_mul_f32_e32 v216, s96, v216
	v_mul_f32_e32 v217, s97, v217
	v_mul_f32_e32 v216, s28, v216
	v_mul_f32_e32 v217, s29, v217
	v_exp_f32_e32 v216, v216
	v_exp_f32_e32 v217, v217
	s_nop 0
	v_add_f32_e32 v216, 1.0, v216
	v_add_f32_e32 v217, 1.0, v217
	v_rcp_f32_e32 v216, v216
	v_rcp_f32_e32 v217, v217
	s_nop 0
	v_mul_f32_e32 v214, v214, v216
	v_mul_f32_e32 v215, v215, v217
	v_mul_f32_e32 v214, v80, v214
	v_mul_f32_e32 v215, v81, v215
	v_cvt_pk_bf16_f32 v77, v214, v215
	global_store_dwordx4 v242, v[74:77], s[6:7]
	v_mov_b32_dpp v210, v34 row_ror:1 row_mask:0xf bank_mask:0xf
	v_mov_b32_dpp v212, v34 row_ror:2 row_mask:0xf bank_mask:0xf
	v_mov_b32_dpp v211, v35 row_ror:1 row_mask:0xf bank_mask:0xf
	v_mov_b32_dpp v213, v35 row_ror:2 row_mask:0xf bank_mask:0xf
	s_nop 1
	v_mov_b32_dpp v210, v50 row_shr:1 row_mask:0xf bank_mask:0xf
	v_mov_b32_dpp v212, v50 row_shr:2 row_mask:0xf bank_mask:0xf
	v_mov_b32_dpp v211, v51 row_shr:1 row_mask:0xf bank_mask:0xf
	v_mov_b32_dpp v213, v51 row_shr:2 row_mask:0xf bank_mask:0xf
	s_nop 1
	v_mul_f32_e32 v210, v186, v210
	v_mul_f32_e32 v211, v187, v211
	v_fma_f32 v214, v194, v50, v210
	v_fma_f32 v215, v195, v51, v211
	v_fma_f32 v214, v178, v212, v214
	v_fma_f32 v215, v179, v213, v215
	v_add_f32_e32 v214, v202, v214
	v_add_f32_e32 v215, v203, v215
	v_mul_f32_e32 v216, s92, v214
	v_mul_f32_e32 v217, s93, v215
	v_mul_f32_e32 v216, v214, v216
	v_mul_f32_e32 v217, v215, v217
	v_fma_f32 v216, v214, v216, v214
	v_fma_f32 v217, v215, v217, v215
	v_mul_f32_e32 v216, s96, v216
	v_mul_f32_e32 v217, s97, v217
	v_mul_f32_e32 v216, s28, v216
	v_mul_f32_e32 v217, s29, v217
	v_exp_f32_e32 v216, v216
	v_exp_f32_e32 v217, v217
	s_nop 0
	v_add_f32_e32 v216, 1.0, v216
	v_add_f32_e32 v217, 1.0, v217
	v_rcp_f32_e32 v216, v216
	v_rcp_f32_e32 v217, v217
	s_nop 0
	v_mul_f32_e32 v214, v214, v216
	v_mul_f32_e32 v215, v215, v217
	v_mul_f32_e32 v214, v58, v214
	v_mul_f32_e32 v215, v59, v215
	v_cvt_pk_bf16_f32 v58, v214, v215
	v_mov_b32_dpp v210, v36 row_ror:1 row_mask:0xf bank_mask:0xf
	v_mov_b32_dpp v212, v36 row_ror:2 row_mask:0xf bank_mask:0xf
	v_mov_b32_dpp v211, v37 row_ror:1 row_mask:0xf bank_mask:0xf
	v_mov_b32_dpp v213, v37 row_ror:2 row_mask:0xf bank_mask:0xf
	s_nop 1
	v_mov_b32_dpp v210, v52 row_shr:1 row_mask:0xf bank_mask:0xf
	v_mov_b32_dpp v212, v52 row_shr:2 row_mask:0xf bank_mask:0xf
	v_mov_b32_dpp v211, v53 row_shr:1 row_mask:0xf bank_mask:0xf
	v_mov_b32_dpp v213, v53 row_shr:2 row_mask:0xf bank_mask:0xf
	s_nop 1
	v_mul_f32_e32 v210, v188, v210
	v_mul_f32_e32 v211, v189, v211
	v_fma_f32 v214, v196, v52, v210
	v_fma_f32 v215, v197, v53, v211
	v_fma_f32 v214, v180, v212, v214
	v_fma_f32 v215, v181, v213, v215
	v_add_f32_e32 v214, v204, v214
	v_add_f32_e32 v215, v205, v215
	v_mul_f32_e32 v216, s92, v214
	v_mul_f32_e32 v217, s93, v215
	v_mul_f32_e32 v216, v214, v216
	v_mul_f32_e32 v217, v215, v217
	v_fma_f32 v216, v214, v216, v214
	v_fma_f32 v217, v215, v217, v215
	v_mul_f32_e32 v216, s96, v216
	v_mul_f32_e32 v217, s97, v217
	v_mul_f32_e32 v216, s28, v216
	v_mul_f32_e32 v217, s29, v217
	v_exp_f32_e32 v216, v216
	v_exp_f32_e32 v217, v217
	s_nop 0
	v_add_f32_e32 v216, 1.0, v216
	v_add_f32_e32 v217, 1.0, v217
	v_rcp_f32_e32 v216, v216
	v_rcp_f32_e32 v217, v217
	s_nop 0
	v_mul_f32_e32 v214, v214, v216
	v_mul_f32_e32 v215, v215, v217
	v_mul_f32_e32 v214, v60, v214
	v_mul_f32_e32 v215, v61, v215
	v_cvt_pk_bf16_f32 v59, v214, v215
	v_mov_b32_dpp v210, v38 row_ror:1 row_mask:0xf bank_mask:0xf
	v_mov_b32_dpp v212, v38 row_ror:2 row_mask:0xf bank_mask:0xf
	v_mov_b32_dpp v211, v39 row_ror:1 row_mask:0xf bank_mask:0xf
	v_mov_b32_dpp v213, v39 row_ror:2 row_mask:0xf bank_mask:0xf
	s_nop 1
	v_mov_b32_dpp v210, v54 row_shr:1 row_mask:0xf bank_mask:0xf
	v_mov_b32_dpp v212, v54 row_shr:2 row_mask:0xf bank_mask:0xf
	v_mov_b32_dpp v211, v55 row_shr:1 row_mask:0xf bank_mask:0xf
	v_mov_b32_dpp v213, v55 row_shr:2 row_mask:0xf bank_mask:0xf
	s_nop 1
	v_mul_f32_e32 v210, v190, v210
	v_mul_f32_e32 v211, v191, v211
	v_fma_f32 v214, v198, v54, v210
	v_fma_f32 v215, v199, v55, v211
	v_fma_f32 v214, v182, v212, v214
	v_fma_f32 v215, v183, v213, v215
	v_add_f32_e32 v214, v206, v214
	v_add_f32_e32 v215, v207, v215
	v_mul_f32_e32 v216, s92, v214
	v_mul_f32_e32 v217, s93, v215
	v_mul_f32_e32 v216, v214, v216
	v_mul_f32_e32 v217, v215, v217
	v_fma_f32 v216, v214, v216, v214
	v_fma_f32 v217, v215, v217, v215
	v_mul_f32_e32 v216, s96, v216
	v_mul_f32_e32 v217, s97, v217
	v_mul_f32_e32 v216, s28, v216
	v_mul_f32_e32 v217, s29, v217
	v_exp_f32_e32 v216, v216
	v_exp_f32_e32 v217, v217
	s_nop 0
	v_add_f32_e32 v216, 1.0, v216
	v_add_f32_e32 v217, 1.0, v217
	v_rcp_f32_e32 v216, v216
	v_rcp_f32_e32 v217, v217
	s_nop 0
	v_mul_f32_e32 v214, v214, v216
	v_mul_f32_e32 v215, v215, v217
	v_mul_f32_e32 v214, v62, v214
	v_mul_f32_e32 v215, v63, v215
	v_cvt_pk_bf16_f32 v60, v214, v215
	v_mov_b32_dpp v210, v40 row_ror:1 row_mask:0xf bank_mask:0xf
	v_mov_b32_dpp v212, v40 row_ror:2 row_mask:0xf bank_mask:0xf
	v_mov_b32_dpp v211, v41 row_ror:1 row_mask:0xf bank_mask:0xf
	v_mov_b32_dpp v213, v41 row_ror:2 row_mask:0xf bank_mask:0xf
	s_nop 1
	v_mov_b32_dpp v210, v56 row_shr:1 row_mask:0xf bank_mask:0xf
	v_mov_b32_dpp v212, v56 row_shr:2 row_mask:0xf bank_mask:0xf
	v_mov_b32_dpp v211, v57 row_shr:1 row_mask:0xf bank_mask:0xf
	v_mov_b32_dpp v213, v57 row_shr:2 row_mask:0xf bank_mask:0xf
	s_nop 1
	v_mul_f32_e32 v210, v192, v210
	v_mul_f32_e32 v211, v193, v211
	v_fma_f32 v214, v200, v56, v210
	v_fma_f32 v215, v201, v57, v211
	v_fma_f32 v214, v184, v212, v214
	v_fma_f32 v215, v185, v213, v215
	v_add_f32_e32 v214, v208, v214
	v_add_f32_e32 v215, v209, v215
	v_mul_f32_e32 v216, s92, v214
	v_mul_f32_e32 v217, s93, v215
	v_mul_f32_e32 v216, v214, v216
	v_mul_f32_e32 v217, v215, v217
	v_fma_f32 v216, v214, v216, v214
	v_fma_f32 v217, v215, v217, v215
	v_mul_f32_e32 v216, s96, v216
	v_mul_f32_e32 v217, s97, v217
	v_mul_f32_e32 v216, s28, v216
	v_mul_f32_e32 v217, s29, v217
	v_exp_f32_e32 v216, v216
	v_exp_f32_e32 v217, v217
	s_nop 0
	v_add_f32_e32 v216, 1.0, v216
	v_add_f32_e32 v217, 1.0, v217
	v_rcp_f32_e32 v216, v216
	v_rcp_f32_e32 v217, v217
	s_nop 0
	v_mul_f32_e32 v214, v214, v216
	v_mul_f32_e32 v215, v215, v217
	v_mul_f32_e32 v214, v64, v214
	v_mul_f32_e32 v215, v65, v215
	v_cvt_pk_bf16_f32 v61, v214, v215
	global_store_dwordx4 v242, v[58:61], s[18:19] offset:3072
	v_mov_b32_dpp v210, v18 row_ror:1 row_mask:0xf bank_mask:0xf
	v_mov_b32_dpp v212, v18 row_ror:2 row_mask:0xf bank_mask:0xf
	v_mov_b32_dpp v211, v19 row_ror:1 row_mask:0xf bank_mask:0xf
	v_mov_b32_dpp v213, v19 row_ror:2 row_mask:0xf bank_mask:0xf
	s_nop 1
	v_mov_b32_dpp v210, v34 row_shr:1 row_mask:0xf bank_mask:0xf
	v_mov_b32_dpp v212, v34 row_shr:2 row_mask:0xf bank_mask:0xf
	v_mov_b32_dpp v211, v35 row_shr:1 row_mask:0xf bank_mask:0xf
	v_mov_b32_dpp v213, v35 row_shr:2 row_mask:0xf bank_mask:0xf
	s_nop 1
	v_mul_f32_e32 v210, v186, v210
	v_mul_f32_e32 v211, v187, v211
	v_fma_f32 v214, v194, v34, v210
	v_fma_f32 v215, v195, v35, v211
	v_fma_f32 v214, v178, v212, v214
	v_fma_f32 v215, v179, v213, v215
	v_add_f32_e32 v214, v202, v214
	v_add_f32_e32 v215, v203, v215
	v_mul_f32_e32 v216, s92, v214
	v_mul_f32_e32 v217, s93, v215
	v_mul_f32_e32 v216, v214, v216
	v_mul_f32_e32 v217, v215, v217
	v_fma_f32 v216, v214, v216, v214
	v_fma_f32 v217, v215, v217, v215
	v_mul_f32_e32 v216, s96, v216
	v_mul_f32_e32 v217, s97, v217
	v_mul_f32_e32 v216, s28, v216
	v_mul_f32_e32 v217, s29, v217
	v_exp_f32_e32 v216, v216
	v_exp_f32_e32 v217, v217
	s_nop 0
	v_add_f32_e32 v216, 1.0, v216
	v_add_f32_e32 v217, 1.0, v217
	v_rcp_f32_e32 v216, v216
	v_rcp_f32_e32 v217, v217
	s_nop 0
	v_mul_f32_e32 v214, v214, v216
	v_mul_f32_e32 v215, v215, v217
	v_mul_f32_e32 v214, v42, v214
	v_mul_f32_e32 v215, v43, v215
	v_cvt_pk_bf16_f32 v42, v214, v215
	v_mov_b32_dpp v210, v20 row_ror:1 row_mask:0xf bank_mask:0xf
	v_mov_b32_dpp v212, v20 row_ror:2 row_mask:0xf bank_mask:0xf
	v_mov_b32_dpp v211, v21 row_ror:1 row_mask:0xf bank_mask:0xf
	v_mov_b32_dpp v213, v21 row_ror:2 row_mask:0xf bank_mask:0xf
	s_nop 1
	v_mov_b32_dpp v210, v36 row_shr:1 row_mask:0xf bank_mask:0xf
	v_mov_b32_dpp v212, v36 row_shr:2 row_mask:0xf bank_mask:0xf
	v_mov_b32_dpp v211, v37 row_shr:1 row_mask:0xf bank_mask:0xf
	v_mov_b32_dpp v213, v37 row_shr:2 row_mask:0xf bank_mask:0xf
	s_nop 1
	v_mul_f32_e32 v210, v188, v210
	v_mul_f32_e32 v211, v189, v211
	v_fma_f32 v214, v196, v36, v210
	v_fma_f32 v215, v197, v37, v211
	v_fma_f32 v214, v180, v212, v214
	v_fma_f32 v215, v181, v213, v215
	v_add_f32_e32 v214, v204, v214
	v_add_f32_e32 v215, v205, v215
	v_mul_f32_e32 v216, s92, v214
	v_mul_f32_e32 v217, s93, v215
	v_mul_f32_e32 v216, v214, v216
	v_mul_f32_e32 v217, v215, v217
	v_fma_f32 v216, v214, v216, v214
	v_fma_f32 v217, v215, v217, v215
	v_mul_f32_e32 v216, s96, v216
	v_mul_f32_e32 v217, s97, v217
	v_mul_f32_e32 v216, s28, v216
	v_mul_f32_e32 v217, s29, v217
	v_exp_f32_e32 v216, v216
	v_exp_f32_e32 v217, v217
	s_nop 0
	v_add_f32_e32 v216, 1.0, v216
	v_add_f32_e32 v217, 1.0, v217
	v_rcp_f32_e32 v216, v216
	v_rcp_f32_e32 v217, v217
	s_nop 0
	v_mul_f32_e32 v214, v214, v216
	v_mul_f32_e32 v215, v215, v217
	v_mul_f32_e32 v214, v44, v214
	v_mul_f32_e32 v215, v45, v215
	v_cvt_pk_bf16_f32 v43, v214, v215
	v_mov_b32_dpp v210, v22 row_ror:1 row_mask:0xf bank_mask:0xf
	v_mov_b32_dpp v212, v22 row_ror:2 row_mask:0xf bank_mask:0xf
	v_mov_b32_dpp v211, v23 row_ror:1 row_mask:0xf bank_mask:0xf
	v_mov_b32_dpp v213, v23 row_ror:2 row_mask:0xf bank_mask:0xf
	s_nop 1
	v_mov_b32_dpp v210, v38 row_shr:1 row_mask:0xf bank_mask:0xf
	v_mov_b32_dpp v212, v38 row_shr:2 row_mask:0xf bank_mask:0xf
	v_mov_b32_dpp v211, v39 row_shr:1 row_mask:0xf bank_mask:0xf
	v_mov_b32_dpp v213, v39 row_shr:2 row_mask:0xf bank_mask:0xf
	s_nop 1
	v_mul_f32_e32 v210, v190, v210
	v_mul_f32_e32 v211, v191, v211
	v_fma_f32 v214, v198, v38, v210
	v_fma_f32 v215, v199, v39, v211
	v_fma_f32 v214, v182, v212, v214
	v_fma_f32 v215, v183, v213, v215
	v_add_f32_e32 v214, v206, v214
	v_add_f32_e32 v215, v207, v215
	v_mul_f32_e32 v216, s92, v214
	v_mul_f32_e32 v217, s93, v215
	v_mul_f32_e32 v216, v214, v216
	v_mul_f32_e32 v217, v215, v217
	v_fma_f32 v216, v214, v216, v214
	v_fma_f32 v217, v215, v217, v215
	v_mul_f32_e32 v216, s96, v216
	v_mul_f32_e32 v217, s97, v217
	v_mul_f32_e32 v216, s28, v216
	v_mul_f32_e32 v217, s29, v217
	v_exp_f32_e32 v216, v216
	v_exp_f32_e32 v217, v217
	s_nop 0
	v_add_f32_e32 v216, 1.0, v216
	v_add_f32_e32 v217, 1.0, v217
	v_rcp_f32_e32 v216, v216
	v_rcp_f32_e32 v217, v217
	s_nop 0
	v_mul_f32_e32 v214, v214, v216
	v_mul_f32_e32 v215, v215, v217
	v_mul_f32_e32 v214, v46, v214
	v_mul_f32_e32 v215, v47, v215
	v_cvt_pk_bf16_f32 v44, v214, v215
	v_mov_b32_dpp v210, v24 row_ror:1 row_mask:0xf bank_mask:0xf
	v_mov_b32_dpp v212, v24 row_ror:2 row_mask:0xf bank_mask:0xf
	v_mov_b32_dpp v211, v25 row_ror:1 row_mask:0xf bank_mask:0xf
	v_mov_b32_dpp v213, v25 row_ror:2 row_mask:0xf bank_mask:0xf
	s_nop 1
	v_mov_b32_dpp v210, v40 row_shr:1 row_mask:0xf bank_mask:0xf
	v_mov_b32_dpp v212, v40 row_shr:2 row_mask:0xf bank_mask:0xf
	v_mov_b32_dpp v211, v41 row_shr:1 row_mask:0xf bank_mask:0xf
	v_mov_b32_dpp v213, v41 row_shr:2 row_mask:0xf bank_mask:0xf
	s_nop 1
	v_mul_f32_e32 v210, v192, v210
	v_mul_f32_e32 v211, v193, v211
	v_fma_f32 v214, v200, v40, v210
	v_fma_f32 v215, v201, v41, v211
	v_fma_f32 v214, v184, v212, v214
	v_fma_f32 v215, v185, v213, v215
	v_add_f32_e32 v214, v208, v214
	v_add_f32_e32 v215, v209, v215
	v_mul_f32_e32 v216, s92, v214
	v_mul_f32_e32 v217, s93, v215
	v_mul_f32_e32 v216, v214, v216
	v_mul_f32_e32 v217, v215, v217
	v_fma_f32 v216, v214, v216, v214
	v_fma_f32 v217, v215, v217, v215
	v_mul_f32_e32 v216, s96, v216
	v_mul_f32_e32 v217, s97, v217
	v_mul_f32_e32 v216, s28, v216
	v_mul_f32_e32 v217, s29, v217
	v_exp_f32_e32 v216, v216
	v_exp_f32_e32 v217, v217
	s_nop 0
	v_add_f32_e32 v216, 1.0, v216
	v_add_f32_e32 v217, 1.0, v217
	v_rcp_f32_e32 v216, v216
	v_rcp_f32_e32 v217, v217
	s_nop 0
	v_mul_f32_e32 v214, v214, v216
	v_mul_f32_e32 v215, v215, v217
	v_mul_f32_e32 v214, v48, v214
	v_mul_f32_e32 v215, v49, v215
	v_cvt_pk_bf16_f32 v45, v214, v215
	global_store_dwordx4 v242, v[42:45], s[18:19] offset:2048
	v_mov_b32_dpp v210, v2 row_ror:1 row_mask:0xf bank_mask:0xf
	v_mov_b32_dpp v212, v2 row_ror:2 row_mask:0xf bank_mask:0xf
	v_mov_b32_dpp v211, v3 row_ror:1 row_mask:0xf bank_mask:0xf
	v_mov_b32_dpp v213, v3 row_ror:2 row_mask:0xf bank_mask:0xf
	s_nop 1
	v_mov_b32_dpp v210, v18 row_shr:1 row_mask:0xf bank_mask:0xf
	v_mov_b32_dpp v212, v18 row_shr:2 row_mask:0xf bank_mask:0xf
	v_mov_b32_dpp v211, v19 row_shr:1 row_mask:0xf bank_mask:0xf
	v_mov_b32_dpp v213, v19 row_shr:2 row_mask:0xf bank_mask:0xf
	s_nop 1
	v_mul_f32_e32 v210, v186, v210
	v_mul_f32_e32 v211, v187, v211
	v_fma_f32 v214, v194, v18, v210
	v_fma_f32 v215, v195, v19, v211
	v_fma_f32 v214, v178, v212, v214
	v_fma_f32 v215, v179, v213, v215
	v_add_f32_e32 v214, v202, v214
	v_add_f32_e32 v215, v203, v215
	v_mul_f32_e32 v216, s92, v214
	v_mul_f32_e32 v217, s93, v215
	v_mul_f32_e32 v216, v214, v216
	v_mul_f32_e32 v217, v215, v217
	v_fma_f32 v216, v214, v216, v214
	v_fma_f32 v217, v215, v217, v215
	v_mul_f32_e32 v216, s96, v216
	v_mul_f32_e32 v217, s97, v217
	v_mul_f32_e32 v216, s28, v216
	v_mul_f32_e32 v217, s29, v217
	v_exp_f32_e32 v216, v216
	v_exp_f32_e32 v217, v217
	s_nop 0
	v_add_f32_e32 v216, 1.0, v216
	v_add_f32_e32 v217, 1.0, v217
	v_rcp_f32_e32 v216, v216
	v_rcp_f32_e32 v217, v217
	s_nop 0
	v_mul_f32_e32 v214, v214, v216
	v_mul_f32_e32 v215, v215, v217
	v_mul_f32_e32 v214, v26, v214
	v_mul_f32_e32 v215, v27, v215
	v_cvt_pk_bf16_f32 v26, v214, v215
	v_mov_b32_dpp v210, v4 row_ror:1 row_mask:0xf bank_mask:0xf
	v_mov_b32_dpp v212, v4 row_ror:2 row_mask:0xf bank_mask:0xf
	v_mov_b32_dpp v211, v5 row_ror:1 row_mask:0xf bank_mask:0xf
	v_mov_b32_dpp v213, v5 row_ror:2 row_mask:0xf bank_mask:0xf
	s_nop 1
	v_mov_b32_dpp v210, v20 row_shr:1 row_mask:0xf bank_mask:0xf
	v_mov_b32_dpp v212, v20 row_shr:2 row_mask:0xf bank_mask:0xf
	v_mov_b32_dpp v211, v21 row_shr:1 row_mask:0xf bank_mask:0xf
	v_mov_b32_dpp v213, v21 row_shr:2 row_mask:0xf bank_mask:0xf
	s_nop 1
	v_mul_f32_e32 v210, v188, v210
	v_mul_f32_e32 v211, v189, v211
	v_fma_f32 v214, v196, v20, v210
	v_fma_f32 v215, v197, v21, v211
	v_fma_f32 v214, v180, v212, v214
	v_fma_f32 v215, v181, v213, v215
	v_add_f32_e32 v214, v204, v214
	v_add_f32_e32 v215, v205, v215
	v_mul_f32_e32 v216, s92, v214
	v_mul_f32_e32 v217, s93, v215
	v_mul_f32_e32 v216, v214, v216
	v_mul_f32_e32 v217, v215, v217
	v_fma_f32 v216, v214, v216, v214
	v_fma_f32 v217, v215, v217, v215
	v_mul_f32_e32 v216, s96, v216
	v_mul_f32_e32 v217, s97, v217
	v_mul_f32_e32 v216, s28, v216
	v_mul_f32_e32 v217, s29, v217
	v_exp_f32_e32 v216, v216
	v_exp_f32_e32 v217, v217
	s_nop 0
	v_add_f32_e32 v216, 1.0, v216
	v_add_f32_e32 v217, 1.0, v217
	v_rcp_f32_e32 v216, v216
	v_rcp_f32_e32 v217, v217
	s_nop 0
	v_mul_f32_e32 v214, v214, v216
	v_mul_f32_e32 v215, v215, v217
	v_mul_f32_e32 v214, v28, v214
	v_mul_f32_e32 v215, v29, v215
	v_cvt_pk_bf16_f32 v27, v214, v215
	v_mov_b32_dpp v210, v6 row_ror:1 row_mask:0xf bank_mask:0xf
	v_mov_b32_dpp v212, v6 row_ror:2 row_mask:0xf bank_mask:0xf
	v_mov_b32_dpp v211, v7 row_ror:1 row_mask:0xf bank_mask:0xf
	v_mov_b32_dpp v213, v7 row_ror:2 row_mask:0xf bank_mask:0xf
	s_nop 1
	v_mov_b32_dpp v210, v22 row_shr:1 row_mask:0xf bank_mask:0xf
	v_mov_b32_dpp v212, v22 row_shr:2 row_mask:0xf bank_mask:0xf
	v_mov_b32_dpp v211, v23 row_shr:1 row_mask:0xf bank_mask:0xf
	v_mov_b32_dpp v213, v23 row_shr:2 row_mask:0xf bank_mask:0xf
	s_nop 1
	v_mul_f32_e32 v210, v190, v210
	v_mul_f32_e32 v211, v191, v211
	v_fma_f32 v214, v198, v22, v210
	v_fma_f32 v215, v199, v23, v211
	v_fma_f32 v214, v182, v212, v214
	v_fma_f32 v215, v183, v213, v215
	v_add_f32_e32 v214, v206, v214
	v_add_f32_e32 v215, v207, v215
	v_mul_f32_e32 v216, s92, v214
	v_mul_f32_e32 v217, s93, v215
	v_mul_f32_e32 v216, v214, v216
	v_mul_f32_e32 v217, v215, v217
	v_fma_f32 v216, v214, v216, v214
	v_fma_f32 v217, v215, v217, v215
	v_mul_f32_e32 v216, s96, v216
	v_mul_f32_e32 v217, s97, v217
	v_mul_f32_e32 v216, s28, v216
	v_mul_f32_e32 v217, s29, v217
	v_exp_f32_e32 v216, v216
	v_exp_f32_e32 v217, v217
	s_nop 0
	v_add_f32_e32 v216, 1.0, v216
	v_add_f32_e32 v217, 1.0, v217
	v_rcp_f32_e32 v216, v216
	v_rcp_f32_e32 v217, v217
	s_nop 0
	v_mul_f32_e32 v214, v214, v216
	v_mul_f32_e32 v215, v215, v217
	v_mul_f32_e32 v214, v30, v214
	v_mul_f32_e32 v215, v31, v215
	v_cvt_pk_bf16_f32 v28, v214, v215
	v_mov_b32_dpp v210, v8 row_ror:1 row_mask:0xf bank_mask:0xf
	v_mov_b32_dpp v212, v8 row_ror:2 row_mask:0xf bank_mask:0xf
	v_mov_b32_dpp v211, v9 row_ror:1 row_mask:0xf bank_mask:0xf
	v_mov_b32_dpp v213, v9 row_ror:2 row_mask:0xf bank_mask:0xf
	s_nop 1
	v_mov_b32_dpp v210, v24 row_shr:1 row_mask:0xf bank_mask:0xf
	v_mov_b32_dpp v212, v24 row_shr:2 row_mask:0xf bank_mask:0xf
	v_mov_b32_dpp v211, v25 row_shr:1 row_mask:0xf bank_mask:0xf
	v_mov_b32_dpp v213, v25 row_shr:2 row_mask:0xf bank_mask:0xf
	s_nop 1
	v_mul_f32_e32 v210, v192, v210
	v_mul_f32_e32 v211, v193, v211
	v_fma_f32 v214, v200, v24, v210
	v_fma_f32 v215, v201, v25, v211
	v_fma_f32 v214, v184, v212, v214
	v_fma_f32 v215, v185, v213, v215
	v_add_f32_e32 v214, v208, v214
	v_add_f32_e32 v215, v209, v215
	v_mul_f32_e32 v216, s92, v214
	v_mul_f32_e32 v217, s93, v215
	v_mul_f32_e32 v216, v214, v216
	v_mul_f32_e32 v217, v215, v217
	v_fma_f32 v216, v214, v216, v214
	v_fma_f32 v217, v215, v217, v215
	v_mul_f32_e32 v216, s96, v216
	v_mul_f32_e32 v217, s97, v217
	v_mul_f32_e32 v216, s28, v216
	v_mul_f32_e32 v217, s29, v217
	v_exp_f32_e32 v216, v216
	v_exp_f32_e32 v217, v217
	s_nop 0
	v_add_f32_e32 v216, 1.0, v216
	v_add_f32_e32 v217, 1.0, v217
	v_rcp_f32_e32 v216, v216
	v_rcp_f32_e32 v217, v217
	s_nop 0
	v_mul_f32_e32 v214, v214, v216
	v_mul_f32_e32 v215, v215, v217
	v_mul_f32_e32 v214, v32, v214
	v_mul_f32_e32 v215, v33, v215
	v_cvt_pk_bf16_f32 v29, v214, v215
	global_store_dwordx4 v242, v[26:29], s[18:19] offset:1024
	s_cmp_eq_u32 s42, 0
	s_cbranch_scc0 .Lup_en_pv
	s_cmp_eq_u32 s39, 0
	s_cbranch_scc1 .Lup_en_pv
	s_add_i32 s26, s34, -1
	s_add_i32 s27, s26, 0xfffff600
	s_add_i32 s66, s26, 0x3600
	s_cmpk_lt_u32 s26, 0xa00
	s_cselect_b32 s27, s66, s27
	v_mov_b32_e32 v249, s27
	s_lshl_b32 s26, s26, 12
	v_add_u32_e32 v248, s26, v248
	s_mov_b32 s27, 0

.Lup_en_pv:
	v_mov_b32_dpp v210, v218 row_ror:1 row_mask:0xf bank_mask:0xf
	v_mov_b32_dpp v212, v218 row_ror:2 row_mask:0xf bank_mask:0xf
	v_mov_b32_dpp v211, v219 row_ror:1 row_mask:0xf bank_mask:0xf
	v_mov_b32_dpp v213, v219 row_ror:2 row_mask:0xf bank_mask:0xf
	s_nop 1
	v_mov_b32_dpp v210, v2 row_shr:1 row_mask:0xf bank_mask:0xf
	v_mov_b32_dpp v212, v2 row_shr:2 row_mask:0xf bank_mask:0xf
	v_mov_b32_dpp v211, v3 row_shr:1 row_mask:0xf bank_mask:0xf
	v_mov_b32_dpp v213, v3 row_shr:2 row_mask:0xf bank_mask:0xf
	s_nop 1
	v_mul_f32_e32 v210, v186, v210
	v_mul_f32_e32 v211, v187, v211
	v_fma_f32 v214, v194, v2, v210
	v_fma_f32 v215, v195, v3, v211
	v_fma_f32 v214, v178, v212, v214
	v_fma_f32 v215, v179, v213, v215
	v_add_f32_e32 v214, v202, v214
	v_add_f32_e32 v215, v203, v215
	v_mul_f32_e32 v216, s92, v214
	v_mul_f32_e32 v217, s93, v215
	v_mul_f32_e32 v216, v214, v216
	v_mul_f32_e32 v217, v215, v217
	v_fma_f32 v216, v214, v216, v214
	v_fma_f32 v217, v215, v217, v215
	v_mul_f32_e32 v216, s96, v216
	v_mul_f32_e32 v217, s97, v217
	v_mul_f32_e32 v216, s28, v216
	v_mul_f32_e32 v217, s29, v217
	v_exp_f32_e32 v216, v216
	v_exp_f32_e32 v217, v217
	s_nop 0
	v_add_f32_e32 v216, 1.0, v216
	v_add_f32_e32 v217, 1.0, v217
	v_rcp_f32_e32 v216, v216
	v_rcp_f32_e32 v217, v217
	s_nop 0
	v_mul_f32_e32 v214, v214, v216
	v_mul_f32_e32 v215, v215, v217
	v_mul_f32_e32 v214, v10, v214
	v_mul_f32_e32 v215, v11, v215
	v_cvt_pk_bf16_f32 v10, v214, v215
	v_mov_b32_dpp v210, v220 row_ror:1 row_mask:0xf bank_mask:0xf
	v_mov_b32_dpp v212, v220 row_ror:2 row_mask:0xf bank_mask:0xf
	v_mov_b32_dpp v211, v221 row_ror:1 row_mask:0xf bank_mask:0xf
	v_mov_b32_dpp v213, v221 row_ror:2 row_mask:0xf bank_mask:0xf
	s_nop 1
	v_mov_b32_dpp v210, v4 row_shr:1 row_mask:0xf bank_mask:0xf
	v_mov_b32_dpp v212, v4 row_shr:2 row_mask:0xf bank_mask:0xf
	v_mov_b32_dpp v211, v5 row_shr:1 row_mask:0xf bank_mask:0xf
	v_mov_b32_dpp v213, v5 row_shr:2 row_mask:0xf bank_mask:0xf
	s_nop 1
	v_mul_f32_e32 v210, v188, v210
	v_mul_f32_e32 v211, v189, v211
	v_fma_f32 v214, v196, v4, v210
	v_fma_f32 v215, v197, v5, v211
	v_fma_f32 v214, v180, v212, v214
	v_fma_f32 v215, v181, v213, v215
	v_add_f32_e32 v214, v204, v214
	v_add_f32_e32 v215, v205, v215
	v_mul_f32_e32 v216, s92, v214
	v_mul_f32_e32 v217, s93, v215
	v_mul_f32_e32 v216, v214, v216
	v_mul_f32_e32 v217, v215, v217
	v_fma_f32 v216, v214, v216, v214
	v_fma_f32 v217, v215, v217, v215
	v_mul_f32_e32 v216, s96, v216
	v_mul_f32_e32 v217, s97, v217
	v_mul_f32_e32 v216, s28, v216
	v_mul_f32_e32 v217, s29, v217
	v_exp_f32_e32 v216, v216
	v_exp_f32_e32 v217, v217
	s_nop 0
	v_add_f32_e32 v216, 1.0, v216
	v_add_f32_e32 v217, 1.0, v217
	v_rcp_f32_e32 v216, v216
	v_rcp_f32_e32 v217, v217
	s_nop 0
	v_mul_f32_e32 v214, v214, v216
	v_mul_f32_e32 v215, v215, v217
	v_mul_f32_e32 v214, v12, v214
	v_mul_f32_e32 v215, v13, v215
	v_cvt_pk_bf16_f32 v11, v214, v215
	v_mov_b32_dpp v210, v222 row_ror:1 row_mask:0xf bank_mask:0xf
	v_mov_b32_dpp v212, v222 row_ror:2 row_mask:0xf bank_mask:0xf
	v_mov_b32_dpp v211, v223 row_ror:1 row_mask:0xf bank_mask:0xf
	v_mov_b32_dpp v213, v223 row_ror:2 row_mask:0xf bank_mask:0xf
	s_nop 1
	v_mov_b32_dpp v210, v6 row_shr:1 row_mask:0xf bank_mask:0xf
	v_mov_b32_dpp v212, v6 row_shr:2 row_mask:0xf bank_mask:0xf
	v_mov_b32_dpp v211, v7 row_shr:1 row_mask:0xf bank_mask:0xf
	v_mov_b32_dpp v213, v7 row_shr:2 row_mask:0xf bank_mask:0xf
	s_nop 1
	v_mul_f32_e32 v210, v190, v210
	v_mul_f32_e32 v211, v191, v211
	v_fma_f32 v214, v198, v6, v210
	v_fma_f32 v215, v199, v7, v211
	v_fma_f32 v214, v182, v212, v214
	v_fma_f32 v215, v183, v213, v215
	v_add_f32_e32 v214, v206, v214
	v_add_f32_e32 v215, v207, v215
	v_mul_f32_e32 v216, s92, v214
	v_mul_f32_e32 v217, s93, v215
	v_mul_f32_e32 v216, v214, v216
	v_mul_f32_e32 v217, v215, v217
	v_fma_f32 v216, v214, v216, v214
	v_fma_f32 v217, v215, v217, v215
	v_mul_f32_e32 v216, s96, v216
	v_mul_f32_e32 v217, s97, v217
	v_mul_f32_e32 v216, s28, v216
	v_mul_f32_e32 v217, s29, v217
	v_exp_f32_e32 v216, v216
	v_exp_f32_e32 v217, v217
	s_nop 0
	v_add_f32_e32 v216, 1.0, v216
	v_add_f32_e32 v217, 1.0, v217
	v_rcp_f32_e32 v216, v216
	v_rcp_f32_e32 v217, v217
	s_nop 0
	v_mul_f32_e32 v214, v214, v216
	v_mul_f32_e32 v215, v215, v217
	v_mul_f32_e32 v214, v14, v214
	v_mul_f32_e32 v215, v15, v215
	v_cvt_pk_bf16_f32 v12, v214, v215
	v_mov_b32_dpp v210, v224 row_ror:1 row_mask:0xf bank_mask:0xf
	v_mov_b32_dpp v212, v224 row_ror:2 row_mask:0xf bank_mask:0xf
	v_mov_b32_dpp v211, v225 row_ror:1 row_mask:0xf bank_mask:0xf
	v_mov_b32_dpp v213, v225 row_ror:2 row_mask:0xf bank_mask:0xf
	s_nop 1
	v_mov_b32_dpp v210, v8 row_shr:1 row_mask:0xf bank_mask:0xf
	v_mov_b32_dpp v212, v8 row_shr:2 row_mask:0xf bank_mask:0xf
	v_mov_b32_dpp v211, v9 row_shr:1 row_mask:0xf bank_mask:0xf
	v_mov_b32_dpp v213, v9 row_shr:2 row_mask:0xf bank_mask:0xf
	s_nop 1
	v_mul_f32_e32 v210, v192, v210
	v_mul_f32_e32 v211, v193, v211
	v_fma_f32 v214, v200, v8, v210
	v_fma_f32 v215, v201, v9, v211
	v_fma_f32 v214, v184, v212, v214
	v_fma_f32 v215, v185, v213, v215
	v_add_f32_e32 v214, v208, v214
	v_add_f32_e32 v215, v209, v215
	v_mul_f32_e32 v216, s92, v214
	v_mul_f32_e32 v217, s93, v215
	v_mul_f32_e32 v216, v214, v216
	v_mul_f32_e32 v217, v215, v217
	v_fma_f32 v216, v214, v216, v214
	v_fma_f32 v217, v215, v217, v215
	v_mul_f32_e32 v216, s96, v216
	v_mul_f32_e32 v217, s97, v217
	v_mul_f32_e32 v216, s28, v216
	v_mul_f32_e32 v217, s29, v217
	v_exp_f32_e32 v216, v216
	v_exp_f32_e32 v217, v217
	s_nop 0
	v_add_f32_e32 v216, 1.0, v216
	v_add_f32_e32 v217, 1.0, v217
	v_rcp_f32_e32 v216, v216
	v_rcp_f32_e32 v217, v217
	s_nop 0
	v_mul_f32_e32 v214, v214, v216
	v_mul_f32_e32 v215, v215, v217
	v_mul_f32_e32 v214, v16, v214
	v_mul_f32_e32 v215, v17, v215
	v_cvt_pk_bf16_f32 v13, v214, v215
	global_store_dwordx4 v242, v[10:13], s[18:19]
	s_mov_b32 s34, s38
	s_mov_b32 s35, s30
	s_mov_b32 s36, s31
	s_branch .Lup_tile

.Lup_el_pv:
	v_mov_b32_dpp v210, v218 row_ror:1 row_mask:0xf bank_mask:0xf
	v_mov_b32_dpp v212, v218 row_ror:2 row_mask:0xf bank_mask:0xf
	v_mov_b32_dpp v211, v219 row_ror:1 row_mask:0xf bank_mask:0xf
	v_mov_b32_dpp v213, v219 row_ror:2 row_mask:0xf bank_mask:0xf
	s_nop 1
	v_mov_b32_dpp v210, v2 row_shr:1 row_mask:0xf bank_mask:0xf
	v_mov_b32_dpp v212, v2 row_shr:2 row_mask:0xf bank_mask:0xf
	v_mov_b32_dpp v211, v3 row_shr:1 row_mask:0xf bank_mask:0xf
	v_mov_b32_dpp v213, v3 row_shr:2 row_mask:0xf bank_mask:0xf
	s_nop 1
	v_mul_f32_e32 v210, v186, v210
	v_mul_f32_e32 v211, v187, v211
	v_fma_f32 v214, v194, v2, v210
	v_fma_f32 v215, v195, v3, v211
	v_fma_f32 v214, v178, v212, v214
	v_fma_f32 v215, v179, v213, v215
	v_add_f32_e32 v214, v202, v214
	v_add_f32_e32 v215, v203, v215
	v_mul_f32_e32 v216, s92, v214
	v_mul_f32_e32 v217, s93, v215
	v_mul_f32_e32 v216, v214, v216
	v_mul_f32_e32 v217, v215, v217
	v_fma_f32 v216, v214, v216, v214
	v_fma_f32 v217, v215, v217, v215
	v_mul_f32_e32 v216, s96, v216
	v_mul_f32_e32 v217, s97, v217
	v_mul_f32_e32 v216, s28, v216
	v_mul_f32_e32 v217, s29, v217
	v_exp_f32_e32 v216, v216
	v_exp_f32_e32 v217, v217
	s_nop 0
	v_add_f32_e32 v216, 1.0, v216
	v_add_f32_e32 v217, 1.0, v217
	v_rcp_f32_e32 v216, v216
	v_rcp_f32_e32 v217, v217
	s_nop 0
	v_mul_f32_e32 v214, v214, v216
	v_mul_f32_e32 v215, v215, v217
	v_mul_f32_e32 v214, v10, v214
	v_mul_f32_e32 v215, v11, v215
	v_cvt_pk_bf16_f32 v10, v214, v215
	v_mov_b32_dpp v210, v220 row_ror:1 row_mask:0xf bank_mask:0xf
	v_mov_b32_dpp v212, v220 row_ror:2 row_mask:0xf bank_mask:0xf
	v_mov_b32_dpp v211, v221 row_ror:1 row_mask:0xf bank_mask:0xf
	v_mov_b32_dpp v213, v221 row_ror:2 row_mask:0xf bank_mask:0xf
	s_nop 1
	v_mov_b32_dpp v210, v4 row_shr:1 row_mask:0xf bank_mask:0xf
	v_mov_b32_dpp v212, v4 row_shr:2 row_mask:0xf bank_mask:0xf
	v_mov_b32_dpp v211, v5 row_shr:1 row_mask:0xf bank_mask:0xf
	v_mov_b32_dpp v213, v5 row_shr:2 row_mask:0xf bank_mask:0xf
	s_nop 1
	v_mul_f32_e32 v210, v188, v210
	v_mul_f32_e32 v211, v189, v211
	v_fma_f32 v214, v196, v4, v210
	v_fma_f32 v215, v197, v5, v211
	v_fma_f32 v214, v180, v212, v214
	v_fma_f32 v215, v181, v213, v215
	v_add_f32_e32 v214, v204, v214
	v_add_f32_e32 v215, v205, v215
	v_mul_f32_e32 v216, s92, v214
	v_mul_f32_e32 v217, s93, v215
	v_mul_f32_e32 v216, v214, v216
	v_mul_f32_e32 v217, v215, v217
	v_fma_f32 v216, v214, v216, v214
	v_fma_f32 v217, v215, v217, v215
	v_mul_f32_e32 v216, s96, v216
	v_mul_f32_e32 v217, s97, v217
	v_mul_f32_e32 v216, s28, v216
	v_mul_f32_e32 v217, s29, v217
	v_exp_f32_e32 v216, v216
	v_exp_f32_e32 v217, v217
	s_nop 0
	v_add_f32_e32 v216, 1.0, v216
	v_add_f32_e32 v217, 1.0, v217
	v_rcp_f32_e32 v216, v216
	v_rcp_f32_e32 v217, v217
	s_nop 0
	v_mul_f32_e32 v214, v214, v216
	v_mul_f32_e32 v215, v215, v217
	v_mul_f32_e32 v214, v12, v214
	v_mul_f32_e32 v215, v13, v215
	v_cvt_pk_bf16_f32 v11, v214, v215
	v_mov_b32_dpp v210, v222 row_ror:1 row_mask:0xf bank_mask:0xf
	v_mov_b32_dpp v212, v222 row_ror:2 row_mask:0xf bank_mask:0xf
	v_mov_b32_dpp v211, v223 row_ror:1 row_mask:0xf bank_mask:0xf
	v_mov_b32_dpp v213, v223 row_ror:2 row_mask:0xf bank_mask:0xf
	s_nop 1
	v_mov_b32_dpp v210, v6 row_shr:1 row_mask:0xf bank_mask:0xf
	v_mov_b32_dpp v212, v6 row_shr:2 row_mask:0xf bank_mask:0xf
	v_mov_b32_dpp v211, v7 row_shr:1 row_mask:0xf bank_mask:0xf
	v_mov_b32_dpp v213, v7 row_shr:2 row_mask:0xf bank_mask:0xf
	s_nop 1
	v_mul_f32_e32 v210, v190, v210
	v_mul_f32_e32 v211, v191, v211
	v_fma_f32 v214, v198, v6, v210
	v_fma_f32 v215, v199, v7, v211
	v_fma_f32 v214, v182, v212, v214
	v_fma_f32 v215, v183, v213, v215
	v_add_f32_e32 v214, v206, v214
	v_add_f32_e32 v215, v207, v215
	v_mul_f32_e32 v216, s92, v214
	v_mul_f32_e32 v217, s93, v215
	v_mul_f32_e32 v216, v214, v216
	v_mul_f32_e32 v217, v215, v217
	v_fma_f32 v216, v214, v216, v214
	v_fma_f32 v217, v215, v217, v215
	v_mul_f32_e32 v216, s96, v216
	v_mul_f32_e32 v217, s97, v217
	v_mul_f32_e32 v216, s28, v216
	v_mul_f32_e32 v217, s29, v217
	v_exp_f32_e32 v216, v216
	v_exp_f32_e32 v217, v217
	s_nop 0
	v_add_f32_e32 v216, 1.0, v216
	v_add_f32_e32 v217, 1.0, v217
	v_rcp_f32_e32 v216, v216
	v_rcp_f32_e32 v217, v217
	s_nop 0
	v_mul_f32_e32 v214, v214, v216
	v_mul_f32_e32 v215, v215, v217
	v_mul_f32_e32 v214, v14, v214
	v_mul_f32_e32 v215, v15, v215
	v_cvt_pk_bf16_f32 v12, v214, v215
	v_mov_b32_dpp v210, v224 row_ror:1 row_mask:0xf bank_mask:0xf
	v_mov_b32_dpp v212, v224 row_ror:2 row_mask:0xf bank_mask:0xf
	v_mov_b32_dpp v211, v225 row_ror:1 row_mask:0xf bank_mask:0xf
	v_mov_b32_dpp v213, v225 row_ror:2 row_mask:0xf bank_mask:0xf
	s_nop 1
	v_mov_b32_dpp v210, v8 row_shr:1 row_mask:0xf bank_mask:0xf
	v_mov_b32_dpp v212, v8 row_shr:2 row_mask:0xf bank_mask:0xf
	v_mov_b32_dpp v211, v9 row_shr:1 row_mask:0xf bank_mask:0xf
	v_mov_b32_dpp v213, v9 row_shr:2 row_mask:0xf bank_mask:0xf
	s_nop 1
	v_mul_f32_e32 v210, v192, v210
	v_mul_f32_e32 v211, v193, v211
	v_fma_f32 v214, v200, v8, v210
	v_fma_f32 v215, v201, v9, v211
	v_fma_f32 v214, v184, v212, v214
	v_fma_f32 v215, v185, v213, v215
	v_add_f32_e32 v214, v208, v214
	v_add_f32_e32 v215, v209, v215
	v_mul_f32_e32 v216, s92, v214
	v_mul_f32_e32 v217, s93, v215
	v_mul_f32_e32 v216, v214, v216
	v_mul_f32_e32 v217, v215, v217
	v_fma_f32 v216, v214, v216, v214
	v_fma_f32 v217, v215, v217, v215
	v_mul_f32_e32 v216, s96, v216
	v_mul_f32_e32 v217, s97, v217
	v_mul_f32_e32 v216, s28, v216
	v_mul_f32_e32 v217, s29, v217
	v_exp_f32_e32 v216, v216
	v_exp_f32_e32 v217, v217
	s_nop 0
	v_add_f32_e32 v216, 1.0, v216
	v_add_f32_e32 v217, 1.0, v217
	v_rcp_f32_e32 v216, v216
	v_rcp_f32_e32 v217, v217
	s_nop 0
	v_mul_f32_e32 v214, v214, v216
	v_mul_f32_e32 v215, v215, v217
	v_mul_f32_e32 v214, v16, v214
	v_mul_f32_e32 v215, v17, v215
	v_cvt_pk_bf16_f32 v13, v214, v215
	global_store_dwordx4 v242, v[10:13], s[18:19]
